# P5 layer-0: the freshly written 'out' rows are loaded normally again (nt kept for the cold x rows)
# speedup vs baseline: 1.0460x; 1.0050x over previous
.LBB0_787:
	s_add_i32 s16, s56, s8
	s_cmpk_lt_i32 s16, 0x4000
	s_cselect_b64 s[44:45], -1, 0
	s_and_b64 s[38:39], s[44:45], exec
	s_cselect_b32 s42, s16, s8
	s_add_u32 s40, s26, s28
	s_addc_u32 s41, s27, s29
	s_add_u32 s46, s40, 0x2700000
	s_addc_u32 s47, s41, 0
	s_ashr_i32 s43, s42, 31
	s_lshl_b64 s[38:39], s[42:43], 6
	s_add_u32 s38, s9, s38
	s_addc_u32 s39, s13, s39
	global_load_dwordx4 v[34:37], v1, s[46:47] offset:48
	global_load_dwordx4 v[38:41], v1, s[46:47] offset:32
	global_load_dwordx4 v[42:45], v1, s[46:47] offset:16
	global_load_dwordx4 v[46:49], v229, s[40:41]
	global_load_dwordx4 v[50:53], v1, s[38:39] offset:48
	global_load_dwordx4 v[54:57], v1, s[38:39] offset:32
	global_load_dwordx4 v[70:73], v1, s[38:39] offset:16
	global_load_dwordx4 v[74:77], v1, s[38:39]
	s_lshl_b64 s[46:47], s[42:43], 11
	s_lshl_b64 s[50:51], s[42:43], 12
	s_cmpk_gt_i32 s16, 0x3fff
	s_brev_b32 s16, 16
	v_lshl_add_u64 v[90:91], v[58:59], 0, s[46:47]
	v_lshl_add_u64 v[84:85], v[60:61], 0, s[50:51]
	s_waitcnt vmcnt(6)
	v_add_f32_e32 v38, v38, v39
	v_add_f32_e32 v40, v40, v41
	s_waitcnt vmcnt(4)
	v_mov_b32_e32 v78, v47
	v_mov_b32_e32 v79, v48
	v_mov_b32_e32 v47, v49
	v_mov_b32_e32 v48, v43
	v_mov_b32_e32 v49, v44
	v_mov_b32_e32 v43, v45
	v_pk_add_f32 v[46:47], v[78:79], v[46:47]
	v_pk_add_f32 v[42:43], v[48:49], v[42:43]
	v_pk_add_f32 v[46:47], v[46:47], v[46:47] op_sel:[0,1] op_sel_hi:[1,0]
	v_pk_add_f32 v[42:43], v[42:43], v[42:43] op_sel:[0,1] op_sel_hi:[1,0]
	v_mov_b32_e32 v47, v34
	v_mov_b32_e32 v43, v35
	v_mov_b32_e32 v39, v36
	v_mov_b32_e32 v41, v37
	v_pk_add_f32 v[34:35], v[46:47], v[42:43]
	v_pk_add_f32 v[36:37], v[38:39], v[40:41]
	s_waitcnt vmcnt(2)
	v_add_f32_e32 v38, v54, v55
	v_pk_add_f32 v[34:35], v[34:35], v[36:37]
	s_waitcnt vmcnt(1)
	v_mov_b32_e32 v36, v71
	v_add_f32_e32 v0, v34, v35
	s_waitcnt vmcnt(0)
	v_mov_b32_e32 v34, v75
	v_mov_b32_e32 v35, v76
	v_mov_b32_e32 v75, v77
	v_mov_b32_e32 v37, v72
	v_mov_b32_e32 v71, v73
	v_pk_add_f32 v[34:35], v[34:35], v[74:75]
	v_pk_add_f32 v[36:37], v[36:37], v[70:71]
	v_pk_add_f32 v[34:35], v[34:35], v[34:35] op_sel:[0,1] op_sel_hi:[1,0]
	v_pk_add_f32 v[36:37], v[36:37], v[36:37] op_sel:[0,1] op_sel_hi:[1,0]
	v_add_f32_e32 v40, v56, v57
	v_mov_b32_e32 v35, v50
	v_mov_b32_e32 v37, v51
	v_mov_b32_e32 v39, v52
	v_mov_b32_e32 v41, v53
	v_pk_add_f32 v[34:35], v[34:35], v[36:37]
	v_pk_add_f32 v[36:37], v[38:39], v[40:41]
	v_fmamk_f32 v0, v0, 0x3a800000, v227
	v_pk_add_f32 v[34:35], v[34:35], v[36:37]
	v_cmp_gt_f32_e32 vcc, s7, v0
	v_add_f32_e32 v34, v34, v35
	v_mul_f32_e32 v35, 0x4f800000, v0
	v_cndmask_b32_e32 v0, v0, v35, vcc
	v_sqrt_f32_e32 v35, v0
	v_fmamk_f32 v34, v34, 0x3a800000, v227
	v_cmp_gt_f32_e64 s[38:39], s7, v34
	v_mul_f32_e32 v38, 0x4f800000, v34
	v_add_u32_e32 v37, -1, v35
	v_fma_f32 v41, -v37, v35, v0
	v_add_u32_e32 v36, 1, v35
	v_cmp_ge_f32_e64 s[40:41], 0, v41
	v_cndmask_b32_e64 v34, v34, v38, s[38:39]
	v_sqrt_f32_e32 v38, v34
	v_cndmask_b32_e64 v37, v35, v37, s[40:41]
	v_fma_f32 v35, -v36, v35, v0
	v_cmp_lt_f32_e64 s[40:41], 0, v35
	v_add_u32_e32 v40, -1, v38
	v_add_u32_e32 v39, 1, v38
	v_cndmask_b32_e64 v35, v37, v36, s[40:41]
	v_mul_f32_e32 v36, 0x37800000, v35
	v_cndmask_b32_e32 v35, v35, v36, vcc
	v_cmp_class_f32_e32 vcc, v0, v228
	v_lshl_add_u64 v[70:71], s[26:27], 0, v[68:69]
	s_nop 0
	v_cndmask_b32_e32 v0, v35, v0, vcc
	v_div_scale_f32 v35, s[40:41], v0, v0, 1.0
	v_rcp_f32_e32 v36, v35
	s_nop 0
	v_fma_f32 v37, -v35, v36, 1.0
	v_fmac_f32_e32 v36, v37, v36
	v_div_scale_f32 v37, vcc, 1.0, v0, 1.0
	v_mul_f32_e32 v41, v37, v36
	v_fma_f32 v42, -v35, v41, v37
	v_fmac_f32_e32 v41, v42, v36
	v_fma_f32 v35, -v35, v41, v37
	v_div_fmas_f32 v35, v35, v36, v41
	v_div_fixup_f32 v80, v35, v0, 1.0
	v_fma_f32 v0, -v40, v38, v34
	v_cmp_ge_f32_e32 vcc, 0, v0
	v_fma_f32 v35, -v39, v38, v34
	s_nop 0
	v_cndmask_b32_e32 v0, v38, v40, vcc
	v_cmp_lt_f32_e32 vcc, 0, v35
	s_nop 1
	v_cndmask_b32_e32 v0, v0, v39, vcc
	v_mul_f32_e32 v35, 0x37800000, v0
	v_cndmask_b32_e64 v0, v0, v35, s[38:39]
	v_cmp_class_f32_e32 vcc, v34, v228
	s_nop 1
	v_cndmask_b32_e32 v0, v0, v34, vcc
	v_div_scale_f32 v34, s[38:39], v0, v0, 1.0
	v_rcp_f32_e32 v35, v34
	s_nop 0
	v_fma_f32 v36, -v34, v35, 1.0
	v_fmac_f32_e32 v35, v36, v35
	v_div_scale_f32 v36, vcc, 1.0, v0, 1.0
	v_mul_f32_e32 v37, v36, v35
	v_fma_f32 v38, -v34, v37, v36
	v_fmac_f32_e32 v37, v38, v35
	v_fma_f32 v34, -v34, v37, v36
	v_div_fmas_f32 v34, v34, v35, v37
	v_add_co_u32_e32 v96, vcc, s16, v70
	v_div_fixup_f32 v82, v34, v0, 1.0
	s_nop 0
	v_addc_co_u32_e32 v97, vcc, 0, v71, vcc
	global_load_dwordx4 v[34:37], v[66:67], off nt
	global_load_dwordx4 v[38:41], v[84:85], off nt
	global_load_dwordx2 v[42:43], v[96:97], off
	global_load_dwordx2 v[44:45], v[90:91], off
	v_add_co_u32_e32 v102, vcc, 0xe000000, v70
	s_waitcnt vmcnt(1)
	v_lshlrev_b32_e32 v46, 16, v42
	v_and_b32_e32 v47, 0xffff0000, v42
	v_lshlrev_b32_e32 v42, 16, v43
	v_and_b32_e32 v43, 0xffff0000, v43
	s_waitcnt vmcnt(0)
	v_lshlrev_b32_e32 v48, 16, v44
	v_and_b32_e32 v49, 0xffff0000, v44
	v_lshlrev_b32_e32 v44, 16, v45
	v_and_b32_e32 v45, 0xffff0000, v45
	v_pk_mul_f32 v[46:47], v[80:81], v[46:47] op_sel_hi:[0,1]
	v_pk_mul_f32 v[42:43], v[80:81], v[42:43] op_sel_hi:[0,1]
	v_pk_fma_f32 v[76:77], v[4:5], v[42:43], v[36:37]
	v_pk_fma_f32 v[78:79], v[2:3], v[46:47], v[34:35]
	v_pk_mul_f32 v[34:35], v[82:83], v[48:49] op_sel_hi:[0,1]
	v_pk_mul_f32 v[36:37], v[82:83], v[44:45] op_sel_hi:[0,1]
	v_pk_fma_f32 v[72:73], v[4:5], v[36:37], v[40:41]
	v_pk_fma_f32 v[74:75], v[2:3], v[34:35], v[38:39]
	global_load_dwordx4 v[54:57], v[66:67], off offset:1024 nt
	global_load_dwordx4 v[50:53], v[84:85], off offset:1024 nt
	global_load_dwordx2 v[94:95], v[96:97], off offset:512
	global_load_dwordx2 v[92:93], v[90:91], off offset:512
	global_load_dwordx4 v[46:49], v[66:67], off offset:2048 nt
	global_load_dwordx4 v[42:45], v[84:85], off offset:2048 nt
	global_load_dwordx2 v[88:89], v[96:97], off offset:1024
	global_load_dwordx2 v[86:87], v[90:91], off offset:1024
	global_load_dwordx4 v[38:41], v[66:67], off offset:3072 nt
	global_load_dwordx4 v[34:37], v[84:85], off offset:3072 nt
	s_nop 0
	global_load_dwordx2 v[84:85], v[96:97], off offset:1536
	s_nop 0
	global_load_dwordx2 v[90:91], v[90:91], off offset:1536
	v_lshl_add_u64 v[96:97], v[62:63], 0, s[46:47]
	v_addc_co_u32_e32 v103, vcc, 0, v71, vcc
	v_cvt_pk_bf16_f32 v100, v78, v79
	v_cvt_pk_bf16_f32 v101, v76, v77
	v_cvt_pk_bf16_f32 v98, v74, v75
	v_cvt_pk_bf16_f32 v99, v72, v73
	global_store_dwordx2 v[102:103], v[100:101], off
	s_cbranch_scc1 .LBB0_789
	global_store_dwordx2 v[96:97], v[98:99], off
